# P2 hfold items: second half's four row loads requested with the first half's (16 instead of 32 serialized load round trips per item)
# speedup vs baseline: 1.0028x; 1.0028x over previous
; DEVI float bfe(const uint4& q, int i) { const unsigned wd = (i >> 1) == 0 ? q.x : ((i >> 1) == 1 ? q.y : ((i >> 1) == 2 ? q.z : q.w)); return (i & 1) ? bfhi(wd) : bflo(wd); }
; DEVI void hfold_item(const P& p, int it, float* sm) {
;     ...
;     for (int k = 0; k < 16; ++k) {
;         const int n = nb * 64 + w * 16 + k;
;         const float sgn = (n & 1) ? -1.0f : 1.0f;
;         const int nB = n == 0 ? 0 : 4096 - n;
; #pragma unroll
;         for (int i = 0; i < 2; ++i) {
;             const int j0 = (i * 64 + lane) * 8;
;             const uint4 qa = *(const uint4*)(H + (size_t)n * 1024 + j0), qb = *(const uint4*)(H + (size_t)nB * 1024 + j0);
;             const uint4 qc = *(const uint4*)(H + (size_t)(2048 - n) * 1024 + j0), qd = *(const uint4*)(H + (size_t)(2048 + n) * 1024 + j0);
;             float he[8], ho[8], hqe[8], hqo[8];
; #pragma unroll
;             for (int c = 0; c < 8; ++c) {
;                 const float A = bfe(qa, c), C = bfe(qc, c);
;                 const float B = n == 0 ? 0.f : bfe(qb, c), D = n == 0 ? 0.f : bfe(qd, c);
;                 he[c] = (A + B) + (C + D); ho[c] = (A + B) - (C + D);
;                 hqe[c] = n == 0 ? 0.f : (A - B) - (C - D); hqo[c] = n == 0 ? 0.f : (A - B) + (C - D);
;                 alt[i * 8 + c] += sgn * he[c];
.LBB0_221:
	v_cmp_eq_u32_e32 vcc, s7, v27
	v_or_b32_e32 v40, 0x200000, v55
	v_mov_b32_e32 v41, v17
	v_cndmask_b32_e64 v16, v54, 0, vcc
	v_lshl_add_u64 v[36:37], v[30:31], 0, v[22:23]
	v_lshl_add_u64 v[38:39], v[34:35], 0, v[22:23]
	v_lshl_add_u64 v[72:73], v[16:17], 1, v[28:29]
	global_load_dwordx4 v[56:59], v[36:37], off
	global_load_dwordx4 v[60:63], v[38:39], off
	v_lshl_add_u64 v[74:75], v[40:41], 1, v[28:29]
	global_load_dwordx4 v[64:67], v[72:73], off
	global_load_dwordx4 v[68:71], v[74:75], off
	global_load_dwordx4 v[232:235], v[36:37], off offset:1024
	global_load_dwordx4 v[236:239], v[38:39], off offset:1024
	global_load_dwordx4 v[240:243], v[72:73], off offset:1024
	global_load_dwordx4 v[244:247], v[74:75], off offset:1024
	v_lshl_add_u64 v[42:43], v[32:33], 0, v[22:23]
	v_add_co_u32_e64 v44, s[2:3], s13, v42
	s_bitcmp0_b32 s7, 0
	s_nop 0
	v_addc_co_u32_e64 v45, s[2:3], 0, v43, s[2:3]
	v_add_co_u32_e64 v46, s[2:3], s14, v42
	v_add_u32_e32 v55, 0x400, v55
	s_nop 0
	v_addc_co_u32_e64 v47, s[2:3], 0, v43, s[2:3]
	v_add_co_u32_e64 v40, s[2:3], s15, v42
	v_lshl_add_u64 v[30:31], v[30:31], 0, s[0:1]
	s_nop 0
	v_addc_co_u32_e64 v41, s[2:3], 0, v43, s[2:3]
	v_add_co_u32_e64 v42, s[2:3], s18, v42
	v_lshl_add_u64 v[32:33], v[32:33], 0, s[0:1]
	s_nop 0
	v_addc_co_u32_e64 v43, s[2:3], 0, v43, s[2:3]
	s_cselect_b64 s[2:3], -1, 0
	s_add_i32 s7, s7, 1
	v_lshl_add_u64 v[34:35], v[34:35], 0, s[4:5]
	v_add_u32_e32 v54, 0xfffffc00, v54
	s_cmp_eq_u32 s7, 16
	s_waitcnt vmcnt(7)
	v_lshlrev_b32_e32 v76, 16, v56
	s_waitcnt vmcnt(6)
	v_lshlrev_b32_e32 v78, 16, v60
	s_waitcnt vmcnt(5)
	v_lshlrev_b32_e32 v16, 16, v64
	s_waitcnt vmcnt(4)
	v_lshlrev_b32_e32 v86, 16, v68
	v_and_b32_e32 v87, 0xffff0000, v64
	v_and_b32_e32 v88, 0xffff0000, v68
	v_lshlrev_b32_e32 v90, 16, v65
	v_lshlrev_b32_e32 v92, 16, v69
	v_and_b32_e32 v89, 0xffff0000, v65
	v_and_b32_e32 v91, 0xffff0000, v69
	v_lshlrev_b32_e32 v94, 16, v66
	v_lshlrev_b32_e32 v96, 16, v70
	v_and_b32_e32 v93, 0xffff0000, v66
	v_and_b32_e32 v95, 0xffff0000, v70
	v_lshlrev_b32_e32 v98, 16, v67
	v_lshlrev_b32_e32 v100, 16, v71
	v_and_b32_e32 v97, 0xffff0000, v67
	v_and_b32_e32 v99, 0xffff0000, v71
	v_and_b32_e32 v77, 0xffff0000, v56
	v_and_b32_e32 v79, 0xffff0000, v60
	v_lshlrev_b32_e32 v56, 16, v57
	v_lshlrev_b32_e32 v60, 16, v61
	v_and_b32_e32 v57, 0xffff0000, v57
	v_and_b32_e32 v61, 0xffff0000, v61
	v_lshlrev_b32_e32 v80, 16, v58
	v_lshlrev_b32_e32 v82, 16, v62
	v_and_b32_e32 v81, 0xffff0000, v58
	v_and_b32_e32 v83, 0xffff0000, v62
	v_lshlrev_b32_e32 v58, 16, v59
	v_lshlrev_b32_e32 v62, 16, v63
	v_and_b32_e32 v59, 0xffff0000, v59
	v_and_b32_e32 v63, 0xffff0000, v63
	v_cndmask_b32_e64 v71, v87, 0, vcc
	v_cndmask_b32_e64 v70, v16, 0, vcc
	v_cndmask_b32_e64 v87, v88, 0, vcc
	v_cndmask_b32_e64 v86, v86, 0, vcc
	v_cndmask_b32_e64 v89, v89, 0, vcc
	v_cndmask_b32_e64 v88, v90, 0, vcc
	v_cndmask_b32_e64 v91, v91, 0, vcc
	v_cndmask_b32_e64 v90, v92, 0, vcc
	v_cndmask_b32_e64 v93, v93, 0, vcc
	v_cndmask_b32_e64 v92, v94, 0, vcc
	v_cndmask_b32_e64 v95, v95, 0, vcc
	v_cndmask_b32_e64 v94, v96, 0, vcc
	v_cndmask_b32_e64 v97, v97, 0, vcc
	v_cndmask_b32_e64 v96, v98, 0, vcc
	v_cndmask_b32_e64 v99, v99, 0, vcc
	v_cndmask_b32_e64 v98, v100, 0, vcc
	v_mov_b32_e32 v84, v76
	v_mov_b32_e32 v85, v78
	v_mov_b32_e32 v64, v56
	v_mov_b32_e32 v65, v60
	v_mov_b32_e32 v68, v80
	v_mov_b32_e32 v69, v82
	v_mov_b32_e32 v66, v58
	v_mov_b32_e32 v67, v62
	v_pk_add_f32 v[100:101], v[70:71], v[76:77]
	v_pk_add_f32 v[102:103], v[86:87], v[78:79]
	v_mov_b32_e32 v104, v70
	v_mov_b32_e32 v105, v86
	v_mov_b32_e32 v78, v77
	v_mov_b32_e32 v86, v71
	v_pk_add_f32 v[70:71], v[88:89], v[56:57]
	v_pk_add_f32 v[76:77], v[90:91], v[60:61]
	v_mov_b32_e32 v106, v88
	v_mov_b32_e32 v107, v90
	v_mov_b32_e32 v60, v57
	v_mov_b32_e32 v90, v89
	v_pk_add_f32 v[56:57], v[92:93], v[80:81]
	v_pk_add_f32 v[88:89], v[94:95], v[82:83]
	v_mov_b32_e32 v108, v92
	v_mov_b32_e32 v109, v94
	v_mov_b32_e32 v82, v81
	v_mov_b32_e32 v94, v93
	v_pk_add_f32 v[92:93], v[98:99], v[62:63]
	v_mov_b32_e32 v110, v96
	v_mov_b32_e32 v111, v98
	v_mov_b32_e32 v62, v59
	v_mov_b32_e32 v98, v97
	v_pk_add_f32 v[80:81], v[96:97], v[58:59]
	v_pk_add_f32 v[84:85], v[84:85], v[104:105] neg_lo:[0,1] neg_hi:[0,1]
	v_pk_add_f32 v[78:79], v[78:79], v[86:87] neg_lo:[0,1] neg_hi:[0,1]
	v_pk_add_f32 v[86:87], v[70:71], v[76:77]
	v_pk_add_f32 v[64:65], v[64:65], v[106:107] neg_lo:[0,1] neg_hi:[0,1]
	v_pk_add_f32 v[70:71], v[70:71], v[76:77] neg_lo:[0,1] neg_hi:[0,1]
	v_pk_add_f32 v[60:61], v[60:61], v[90:91] neg_lo:[0,1] neg_hi:[0,1]
	v_pk_add_f32 v[76:77], v[56:57], v[88:89]
	v_pk_add_f32 v[68:69], v[68:69], v[108:109] neg_lo:[0,1] neg_hi:[0,1]
	v_pk_add_f32 v[88:89], v[56:57], v[88:89] neg_lo:[0,1] neg_hi:[0,1]
	v_pk_add_f32 v[56:57], v[82:83], v[94:95] neg_lo:[0,1] neg_hi:[0,1]
	v_pk_add_f32 v[66:67], v[66:67], v[110:111] neg_lo:[0,1] neg_hi:[0,1]
	v_pk_add_f32 v[62:63], v[62:63], v[98:99] neg_lo:[0,1] neg_hi:[0,1]
	v_pk_add_f32 v[58:59], v[100:101], v[102:103]
	v_pk_add_f32 v[96:97], v[100:101], v[102:103] neg_lo:[0,1] neg_hi:[0,1]
	v_pk_add_f32 v[82:83], v[80:81], v[92:93]
	v_pk_add_f32 v[80:81], v[80:81], v[92:93] neg_lo:[0,1] neg_hi:[0,1]
	v_sub_f32_e32 v16, v84, v85
	v_sub_f32_e32 v91, v78, v79
	v_add_f32_e32 v78, v78, v79
	v_sub_f32_e32 v79, v64, v65
	v_add_f32_e32 v92, v64, v65
	v_cndmask_b32_e64 v65, -v87, v87, s[2:3]
	v_cndmask_b32_e64 v64, -v86, v86, s[2:3]
	v_sub_f32_e32 v93, v60, v61
	v_sub_f32_e32 v95, v68, v69
	v_add_f32_e32 v98, v68, v69
	v_cndmask_b32_e64 v69, -v77, v77, s[2:3]
	v_cndmask_b32_e64 v68, -v76, v76, s[2:3]
	v_sub_f32_e32 v99, v56, v57
	v_sub_f32_e32 v101, v66, v67
; DEVI unsigned pk2(float lo, float hi) { f32x2 v = {lo, hi}; bf16x2_t b = __builtin_convertvector(v, bf16x2_t); return __builtin_bit_cast(unsigned, b); }
; DEVI float bfe(const uint4& q, int i) { const unsigned wd = (i >> 1) == 0 ? q.x : ((i >> 1) == 1 ? q.y : ((i >> 1) == 2 ? q.z : q.w)); return (i & 1) ? bfhi(wd) : bflo(wd); }
; DEVI void hfold_item(const P& p, int it, float* sm) {
;     ...
;             const uint4 qa = *(const uint4*)(H + (size_t)n * 1024 + j0), qb = *(const uint4*)(H + (size_t)nB * 1024 + j0);
;             const uint4 qc = *(const uint4*)(H + (size_t)(2048 - n) * 1024 + j0), qd = *(const uint4*)(H + (size_t)(2048 + n) * 1024 + j0);
;             float he[8], ho[8], hqe[8], hqo[8];
; #pragma unroll
;             for (int c = 0; c < 8; ++c) {
;                 const float A = bfe(qa, c), C = bfe(qc, c);
;                 const float B = n == 0 ? 0.f : bfe(qb, c), D = n == 0 ? 0.f : bfe(qd, c);
;                 he[c] = (A + B) + (C + D); ho[c] = (A + B) - (C + D);
;                 hqe[c] = n == 0 ? 0.f : (A - B) - (C - D); hqo[c] = n == 0 ? 0.f : (A - B) + (C - D);
;                 alt[i * 8 + c] += sgn * he[c];
;             }
;             uint4 o;
;             o.x = pk2(he[0], he[1]); o.y = pk2(he[2], he[3]); o.z = pk2(he[4], he[5]); o.w = pk2(he[6], he[7]);
;             *(uint4*)(HF + (size_t)n * 1024 + j0) = o;
;             o.x = pk2(ho[0], ho[1]); o.y = pk2(ho[2], ho[3]); o.z = pk2(ho[4], ho[5]); o.w = pk2(ho[6], ho[7]);
;             *(uint4*)(HF + 1048576 + (size_t)n * 1024 + j0) = o;
;             o.x = pk2(hqe[0], hqe[1]); o.y = pk2(hqe[2], hqe[3]); o.z = pk2(hqe[4], hqe[5]); o.w = pk2(hqe[6], hqe[7]);
;             *(uint4*)(HF + 2 * 1048576 + (size_t)n * 1024 + j0) = o;
;             o.x = pk2(hqo[0], hqo[1]); o.y = pk2(hqo[2], hqo[3]); o.z = pk2(hqo[4], hqo[5]); o.w = pk2(hqo[6], hqo[7]);
;             *(uint4*)(HF + 3 * 1048576 + (size_t)n * 1024 + j0) = o;
	v_sub_f32_e32 v103, v62, v63
	v_add_f32_e32 v90, v84, v85
	v_cndmask_b32_e64 v85, -v59, v59, s[2:3]
	v_cndmask_b32_e64 v84, -v58, v58, s[2:3]
	v_add_f32_e32 v94, v60, v61
	v_add_f32_e32 v100, v56, v57
	v_add_f32_e32 v102, v66, v67
	v_cndmask_b32_e64 v67, -v83, v83, s[2:3]
	v_add_f32_e32 v104, v62, v63
	v_cvt_pk_bf16_f32 v56, v58, v59
	v_cvt_pk_bf16_f32 v57, v86, v87
	v_cvt_pk_bf16_f32 v58, v76, v77
	v_cvt_pk_bf16_f32 v59, v82, v83
	v_cvt_pk_bf16_f32 v61, v70, v71
	v_cvt_pk_bf16_f32 v63, v80, v81
	v_cndmask_b32_e64 v16, v16, 0, vcc
	v_cndmask_b32_e64 v71, v91, 0, vcc
	v_cndmask_b32_e64 v77, v79, 0, vcc
	v_cndmask_b32_e64 v79, v93, 0, vcc
	v_pk_add_f32 v[14:15], v[14:15], v[64:65]
	v_cndmask_b32_e64 v64, v95, 0, vcc
	v_cndmask_b32_e64 v81, v99, 0, vcc
	v_pk_add_f32 v[8:9], v[8:9], v[68:69]
	v_cndmask_b32_e64 v68, v101, 0, vcc
	v_cndmask_b32_e64 v83, v103, 0, vcc
	v_cndmask_b32_e64 v66, -v82, v82, s[2:3]
	v_cvt_pk_bf16_f32 v60, v96, v97
	v_cvt_pk_bf16_f32 v62, v88, v89
	v_cndmask_b32_e64 v70, v90, 0, vcc
	v_cndmask_b32_e64 v76, v78, 0, vcc
	v_pk_add_f32 v[12:13], v[12:13], v[84:85]
	v_cndmask_b32_e64 v78, v92, 0, vcc
	v_cndmask_b32_e64 v80, v94, 0, vcc
	v_cndmask_b32_e64 v65, v98, 0, vcc
	v_cndmask_b32_e64 v82, v100, 0, vcc
	v_cndmask_b32_e64 v69, v102, 0, vcc
	v_cndmask_b32_e64 v84, v104, 0, vcc
	global_store_dwordx4 v[44:45], v[56:59], off
	global_store_dwordx4 v[46:47], v[60:63], off
	v_pk_add_f32 v[10:11], v[10:11], v[66:67]
	v_cvt_pk_bf16_f32 v56, v16, v71
	v_cvt_pk_bf16_f32 v57, v77, v79
	v_cvt_pk_bf16_f32 v58, v64, v81
	v_cvt_pk_bf16_f32 v59, v68, v83
	v_cvt_pk_bf16_f32 v60, v70, v76
	v_cvt_pk_bf16_f32 v61, v78, v80
	v_cvt_pk_bf16_f32 v62, v65, v82
	v_cvt_pk_bf16_f32 v63, v69, v84
	global_store_dwordx4 v[40:41], v[56:59], off
	global_store_dwordx4 v[42:43], v[60:63], off
	s_nop 0
	s_nop 0
	s_waitcnt vmcnt(7)
	v_lshlrev_b32_e32 v68, 16, v232
	s_waitcnt vmcnt(6)
	v_lshlrev_b32_e32 v70, 16, v236
	s_waitcnt vmcnt(5)
	v_lshlrev_b32_e32 v16, 16, v240
	s_waitcnt vmcnt(4)
	v_lshlrev_b32_e32 v72, 16, v244
	v_and_b32_e32 v73, 0xffff0000, v240
	v_and_b32_e32 v74, 0xffff0000, v244
	v_lshlrev_b32_e32 v76, 16, v241
	v_lshlrev_b32_e32 v78, 16, v245
	v_and_b32_e32 v75, 0xffff0000, v241
	v_and_b32_e32 v77, 0xffff0000, v245
	v_lshlrev_b32_e32 v80, 16, v242
	v_lshlrev_b32_e32 v82, 16, v246
	v_and_b32_e32 v81, 0xffff0000, v242
	v_and_b32_e32 v83, 0xffff0000, v246
	v_lshlrev_b32_e32 v86, 16, v243
	v_lshlrev_b32_e32 v88, 16, v247
	v_and_b32_e32 v87, 0xffff0000, v243
	v_and_b32_e32 v89, 0xffff0000, v247
	v_and_b32_e32 v69, 0xffff0000, v232
	v_and_b32_e32 v71, 0xffff0000, v236
	v_lshlrev_b32_e32 v56, 16, v233
	v_lshlrev_b32_e32 v36, 16, v237
	v_and_b32_e32 v57, 0xffff0000, v233
	v_and_b32_e32 v37, 0xffff0000, v237
	v_lshlrev_b32_e32 v60, 16, v234
	v_lshlrev_b32_e32 v64, 16, v238
	v_and_b32_e32 v61, 0xffff0000, v234
	v_and_b32_e32 v65, 0xffff0000, v238
	v_lshlrev_b32_e32 v58, 16, v235
	v_lshlrev_b32_e32 v38, 16, v239
	v_and_b32_e32 v59, 0xffff0000, v235
	v_and_b32_e32 v39, 0xffff0000, v239
	v_cndmask_b32_e64 v63, v73, 0, vcc
	v_cndmask_b32_e64 v62, v16, 0, vcc
	v_cndmask_b32_e64 v67, v74, 0, vcc
	v_cndmask_b32_e64 v66, v72, 0, vcc
	v_cndmask_b32_e64 v75, v75, 0, vcc
	v_cndmask_b32_e64 v74, v76, 0, vcc
	v_cndmask_b32_e64 v77, v77, 0, vcc
	v_cndmask_b32_e64 v76, v78, 0, vcc
	v_cndmask_b32_e64 v81, v81, 0, vcc
	v_cndmask_b32_e64 v80, v80, 0, vcc
	v_cndmask_b32_e64 v83, v83, 0, vcc
	v_cndmask_b32_e64 v82, v82, 0, vcc
	v_cndmask_b32_e64 v87, v87, 0, vcc
	v_cndmask_b32_e64 v86, v86, 0, vcc
	v_cndmask_b32_e64 v89, v89, 0, vcc
	v_cndmask_b32_e64 v88, v88, 0, vcc
	v_mov_b32_e32 v72, v68
	v_mov_b32_e32 v73, v70
	v_mov_b32_e32 v78, v56
	v_mov_b32_e32 v79, v36
	v_mov_b32_e32 v84, v60
	v_mov_b32_e32 v85, v64
	v_mov_b32_e32 v90, v58
	v_mov_b32_e32 v91, v38
	v_pk_add_f32 v[92:93], v[62:63], v[68:69]
	v_pk_add_f32 v[94:95], v[66:67], v[70:71]
	v_mov_b32_e32 v96, v62
	v_mov_b32_e32 v97, v66
	v_mov_b32_e32 v70, v69
	v_mov_b32_e32 v66, v63
	v_pk_add_f32 v[62:63], v[74:75], v[56:57]
	v_pk_add_f32 v[68:69], v[76:77], v[36:37]
	v_mov_b32_e32 v98, v74
	v_mov_b32_e32 v99, v76
	v_mov_b32_e32 v36, v57
	v_mov_b32_e32 v76, v75
	v_pk_add_f32 v[56:57], v[80:81], v[60:61]
	v_pk_add_f32 v[74:75], v[82:83], v[64:65]
	v_mov_b32_e32 v100, v80
	v_mov_b32_e32 v101, v82
	v_mov_b32_e32 v64, v61
	v_mov_b32_e32 v82, v81
	v_pk_add_f32 v[80:81], v[88:89], v[38:39]
	v_mov_b32_e32 v102, v86
	v_mov_b32_e32 v103, v88
	v_mov_b32_e32 v38, v59
	v_mov_b32_e32 v88, v87
	v_pk_add_f32 v[60:61], v[86:87], v[58:59]
	v_pk_add_f32 v[58:59], v[92:93], v[94:95]
	v_pk_add_f32 v[72:73], v[72:73], v[96:97] neg_lo:[0,1] neg_hi:[0,1]
	v_pk_add_f32 v[66:67], v[70:71], v[66:67] neg_lo:[0,1] neg_hi:[0,1]
	v_pk_add_f32 v[70:71], v[62:63], v[68:69]
	v_pk_add_f32 v[78:79], v[78:79], v[98:99] neg_lo:[0,1] neg_hi:[0,1]
	v_pk_add_f32 v[62:63], v[62:63], v[68:69] neg_lo:[0,1] neg_hi:[0,1]
; DEVI float bf2f(bf16_t h) { return __uint_as_float(((unsigned)h) << 16); }
; DEVI unsigned pk2(float lo, float hi) { f32x2 v = {lo, hi}; bf16x2_t b = __builtin_convertvector(v, bf16x2_t); return __builtin_bit_cast(unsigned, b); }
; DEVI void hfold_item(const P& p, int it, float* sm) {
;     ...
;                 he[c] = (A + B) + (C + D); ho[c] = (A + B) - (C + D);
;                 hqe[c] = n == 0 ? 0.f : (A - B) - (C - D); hqo[c] = n == 0 ? 0.f : (A - B) + (C - D);
;                 alt[i * 8 + c] += sgn * he[c];
;             }
;             uint4 o;
;             o.x = pk2(he[0], he[1]); o.y = pk2(he[2], he[3]); o.z = pk2(he[4], he[5]); o.w = pk2(he[6], he[7]);
;             *(uint4*)(HF + (size_t)n * 1024 + j0) = o;
;             o.x = pk2(ho[0], ho[1]); o.y = pk2(ho[2], ho[3]); o.z = pk2(ho[4], ho[5]); o.w = pk2(ho[6], ho[7]);
;             *(uint4*)(HF + 1048576 + (size_t)n * 1024 + j0) = o;
;             o.x = pk2(hqe[0], hqe[1]); o.y = pk2(hqe[2], hqe[3]); o.z = pk2(hqe[4], hqe[5]); o.w = pk2(hqe[6], hqe[7]);
;             *(uint4*)(HF + 2 * 1048576 + (size_t)n * 1024 + j0) = o;
;             o.x = pk2(hqo[0], hqo[1]); o.y = pk2(hqo[2], hqo[3]); o.z = pk2(hqo[4], hqo[5]); o.w = pk2(hqo[6], hqo[7]);
;             *(uint4*)(HF + 3 * 1048576 + (size_t)n * 1024 + j0) = o;
;         }
;     }
;     __syncthreads();
; #pragma unroll
;     for (int i = 0; i < 2; ++i)
; #pragma unroll
;         for (int c = 0; c < 8; ++c) sm[w * 1024 + (i * 64 + lane) * 8 + c] = alt[i * 8 + c];
;     __syncthreads();
;     float* hp = (float*)(p.ws + OFF_HPART) + (size_t)it * 1024;
; #pragma unroll
;     for (int c = 0; c < 4; ++c) { const int j = tid * 4 + c; hp[j] = sm[j] + sm[1024 + j] + sm[2048 + j] + sm[3072 + j]; }
;     if (nb == 0) {
;         float* hs = (float*)(p.ws + OFF_HS) + (size_t)b * 2048;
; #pragma unroll
;         for (int c = 0; c < 4; ++c) {
;             const int j = tid * 4 + c;
;             const float h1 = bf2f(H[(size_t)1024 * 1024 + j]), h3 = bf2f(H[(size_t)3072 * 1024 + j]);
;             hs[j] = h1 + h3; hs[1024 + j] = h1 - h3;
;         }
	v_pk_add_f32 v[36:37], v[36:37], v[76:77] neg_lo:[0,1] neg_hi:[0,1]
	v_pk_add_f32 v[68:69], v[56:57], v[74:75]
	v_pk_add_f32 v[76:77], v[84:85], v[100:101] neg_lo:[0,1] neg_hi:[0,1]
	v_pk_add_f32 v[74:75], v[56:57], v[74:75] neg_lo:[0,1] neg_hi:[0,1]
	v_pk_add_f32 v[56:57], v[64:65], v[82:83] neg_lo:[0,1] neg_hi:[0,1]
	v_pk_add_f32 v[82:83], v[90:91], v[102:103] neg_lo:[0,1] neg_hi:[0,1]
	v_pk_add_f32 v[38:39], v[38:39], v[88:89] neg_lo:[0,1] neg_hi:[0,1]
	v_pk_add_f32 v[86:87], v[92:93], v[94:95] neg_lo:[0,1] neg_hi:[0,1]
	v_pk_add_f32 v[64:65], v[60:61], v[80:81]
	v_pk_add_f32 v[60:61], v[60:61], v[80:81] neg_lo:[0,1] neg_hi:[0,1]
	v_sub_f32_e32 v16, v72, v73
	v_add_f32_e32 v80, v72, v73
	v_cndmask_b32_e64 v73, -v59, v59, s[2:3]
	v_cndmask_b32_e64 v72, -v58, v58, s[2:3]
	v_sub_f32_e32 v81, v66, v67
	v_add_f32_e32 v84, v66, v67
	v_sub_f32_e32 v85, v78, v79
	v_cndmask_b32_e64 v67, -v71, v71, s[2:3]
	v_cndmask_b32_e64 v66, -v70, v70, s[2:3]
	v_sub_f32_e32 v89, v36, v37
	v_sub_f32_e32 v91, v76, v77
	v_sub_f32_e32 v93, v56, v57
	v_sub_f32_e32 v95, v82, v83
	v_add_f32_e32 v82, v82, v83
	v_sub_f32_e32 v83, v38, v39
	v_add_f32_e32 v88, v78, v79
	v_add_f32_e32 v90, v36, v37
	v_add_f32_e32 v92, v76, v77
	v_cndmask_b32_e64 v77, -v69, v69, s[2:3]
	v_cndmask_b32_e64 v76, -v68, v68, s[2:3]
	v_add_f32_e32 v94, v56, v57
	v_cndmask_b32_e64 v79, -v65, v65, s[2:3]
	v_cndmask_b32_e64 v78, -v64, v64, s[2:3]
	v_add_f32_e32 v96, v38, v39
	v_cvt_pk_bf16_f32 v36, v58, v59
	v_cvt_pk_bf16_f32 v37, v70, v71
	v_cvt_pk_bf16_f32 v38, v68, v69
	v_cvt_pk_bf16_f32 v39, v64, v65
	v_cvt_pk_bf16_f32 v57, v62, v63
	v_cvt_pk_bf16_f32 v59, v60, v61
	v_cndmask_b32_e64 v16, v16, 0, vcc
	v_cndmask_b32_e64 v61, v81, 0, vcc
	v_pk_add_f32 v[4:5], v[4:5], v[72:73]
	v_cndmask_b32_e64 v63, v85, 0, vcc
	v_cndmask_b32_e64 v65, v89, 0, vcc
	v_pk_add_f32 v[6:7], v[6:7], v[66:67]
	v_cndmask_b32_e64 v66, v91, 0, vcc
	v_cndmask_b32_e64 v69, v93, 0, vcc
	v_cndmask_b32_e64 v71, v95, 0, vcc
	v_cndmask_b32_e64 v73, v83, 0, vcc
	v_cvt_pk_bf16_f32 v56, v86, v87
	v_cvt_pk_bf16_f32 v58, v74, v75
	v_cndmask_b32_e64 v60, v80, 0, vcc
	v_cndmask_b32_e64 v62, v84, 0, vcc
	v_cndmask_b32_e64 v64, v88, 0, vcc
	v_cndmask_b32_e64 v68, v90, 0, vcc
	v_cndmask_b32_e64 v67, v92, 0, vcc
	v_cndmask_b32_e64 v70, v94, 0, vcc
	v_pk_add_f32 v[0:1], v[0:1], v[76:77]
	v_cndmask_b32_e64 v72, v82, 0, vcc
	v_cndmask_b32_e64 v74, v96, 0, vcc
	v_pk_add_f32 v[2:3], v[2:3], v[78:79]
	global_store_dwordx4 v[44:45], v[36:39], off offset:1024
	global_store_dwordx4 v[46:47], v[56:59], off offset:1024
	v_cvt_pk_bf16_f32 v44, v60, v62
	v_cvt_pk_bf16_f32 v36, v16, v61
	v_cvt_pk_bf16_f32 v37, v63, v65
	v_cvt_pk_bf16_f32 v38, v66, v69
	v_cvt_pk_bf16_f32 v39, v71, v73
	v_cvt_pk_bf16_f32 v45, v64, v68
	v_cvt_pk_bf16_f32 v46, v67, v70
	v_cvt_pk_bf16_f32 v47, v72, v74
	global_store_dwordx4 v[40:41], v[36:39], off offset:1024
	global_store_dwordx4 v[42:43], v[44:47], off offset:1024
	s_cbranch_scc0 .LBB0_221
	s_barrier
	ds_write_b128 v53, v[12:15]
	ds_write_b128 v53, v[8:11] offset:16
	ds_write_b128 v53, v[4:7] offset:2048
	ds_write_b128 v53, v[0:3] offset:2064
	s_waitcnt lgkmcnt(0)
	s_barrier
	ds_read_b128 v[0:3], v48
	ds_read_b128 v[4:7], v48 offset:4096
	ds_read_b128 v[8:11], v48 offset:8192
	ds_read_b128 v[12:15], v48 offset:12288
	s_ashr_i32 s7, s6, 31
	s_and_b32 s16, s6, 15
	s_waitcnt lgkmcnt(2)
	v_pk_add_f32 v[0:1], v[0:1], v[4:5]
	v_pk_add_f32 v[2:3], v[2:3], v[6:7]
	s_lshl_b64 s[2:3], s[6:7], 12
	s_waitcnt lgkmcnt(1)
	v_pk_add_f32 v[0:1], v[0:1], v[8:9]
	v_pk_add_f32 v[2:3], v[2:3], v[10:11]
	v_lshl_add_u64 v[28:29], v[18:19], 0, s[2:3]
	s_waitcnt lgkmcnt(0)
	v_pk_add_f32 v[0:1], v[0:1], v[12:13]
	v_pk_add_f32 v[2:3], v[2:3], v[14:15]
	s_cmp_eq_u32 s16, 0
	global_store_dwordx4 v[28:29], v[0:3], off
	s_cbranch_scc0 .LBB0_219
	v_mov_b32_e32 v27, v17
	v_lshl_add_u64 v[0:1], s[10:11], 0, v[26:27]
	v_add_co_u32_e32 v2, vcc, 0x200000, v0
	s_lshl_b64 s[2:3], s[8:9], 13
	s_nop 0
	v_addc_co_u32_e32 v3, vcc, 0, v1, vcc
	v_add_co_u32_e32 v0, vcc, 0x600000, v0
	global_load_dwordx2 v[2:3], v[2:3], off
	s_nop 0
	v_addc_co_u32_e32 v1, vcc, 0, v1, vcc
	global_load_dwordx2 v[0:1], v[0:1], off
	v_lshl_add_u64 v[8:9], v[20:21], 0, s[2:3]
	v_add_co_u32_e32 v10, vcc, 0x1000, v8
	s_waitcnt vmcnt(1)
	v_and_b32_e32 v5, 0xffff0000, v2
	v_lshlrev_b32_e32 v4, 16, v2
	v_and_b32_e32 v7, 0xffff0000, v3
	v_lshlrev_b32_e32 v6, 16, v3
	s_waitcnt vmcnt(0)
	v_and_b32_e32 v3, 0xffff0000, v0
	v_lshlrev_b32_e32 v2, 16, v0
	v_and_b32_e32 v13, 0xffff0000, v1
	v_lshlrev_b32_e32 v12, 16, v1
	v_pk_add_f32 v[0:1], v[4:5], v[2:3]
	v_pk_add_f32 v[4:5], v[4:5], v[2:3] neg_lo:[0,1] neg_hi:[0,1]
	v_pk_add_f32 v[2:3], v[6:7], v[12:13]
	v_addc_co_u32_e32 v11, vcc, 0, v9, vcc
	v_pk_add_f32 v[6:7], v[6:7], v[12:13] neg_lo:[0,1] neg_hi:[0,1]
	global_store_dwordx4 v[8:9], v[0:3], off
	global_store_dwordx4 v[10:11], v[4:7], off
	s_branch .LBB0_219
